# LayerNorm loop: all gamma/beta loads issued once after the row reductions; the three store-draining vmcnt(0) waits between column blocks removed
# speedup vs baseline: 1.0059x; 1.0030x over previous
; DEVI void ln_phase(const Params& p, const float* g, const float* b, bool whb = true) {
;     ...
;   for (int t0 = gw * 4; t0 < L; t0 += nw * 4) {
;     f32x4 v[4][4];
;     float* h[4];
; #pragma unroll
;     for (int r = 0; r < 4; ++r) {
;       h[r] = hfrow(p, t0 + r);
; #pragma unroll
;       for (int i = 0; i < 4; ++i) v[r][i] = *(const f32x4*)(h[r] + i * 256 + lane * 4);
;     }
;     float s[4], q[4];
; #pragma unroll
;     for (int r = 0; r < 4; ++r) {
;       s[r] = 0.f;
; #pragma unroll
;       for (int i = 0; i < 4; ++i) s[r] += v[r][i][0] + v[r][i][1] + v[r][i][2] + v[r][i][3];
;     }
.LBB0_1581:
	v_add_u32_e32 v0, 16, v78
	v_cmp_lt_i32_e32 vcc, 15, v0
	s_and_saveexec_b64 s[0:1], vcc
	s_xor_b64 s[0:1], exec, s[0:1]
	v_mov_b32_e32 v79, v1
	v_lshlrev_b64 v[2:3], 12, v[78:79]
	v_lshl_add_u64 v[2:3], s[26:27], 0, v[2:3]
	s_andn2_saveexec_b64 s[0:1], s[0:1]
	v_ashrrev_i32_e32 v81, 31, v80
	v_lshl_add_u64 v[2:3], v[80:81], 2, s[36:37]
	s_or_b64 exec, exec, s[0:1]
	v_lshlrev_b32_e32 v0, 2, v72
	v_lshl_add_u64 v[88:89], v[2:3], 0, v[0:1]
	global_load_dwordx4 v[50:53], v[88:89], off
	global_load_dwordx4 v[34:37], v[88:89], off offset:1024
	global_load_dwordx4 v[18:21], v[88:89], off offset:2048
	global_load_dwordx4 v[2:5], v[88:89], off offset:3072
	v_add_u32_e32 v6, 17, v78
	v_cmp_lt_i32_e32 vcc, 15, v6
	s_and_saveexec_b64 s[0:1], vcc
	s_xor_b64 s[0:1], exec, s[0:1]
	v_add_u32_e32 v6, 1, v78
	v_mov_b32_e32 v7, v1
	v_lshlrev_b64 v[6:7], 12, v[6:7]
	v_lshl_add_u64 v[6:7], s[26:27], 0, v[6:7]
	s_andn2_saveexec_b64 s[0:1], s[0:1]
	v_add_u32_e32 v6, 0x400, v80
	v_ashrrev_i32_e32 v7, 31, v6
	v_lshl_add_u64 v[6:7], v[6:7], 2, s[36:37]
	s_or_b64 exec, exec, s[0:1]
	v_lshl_add_u64 v[84:85], v[6:7], 0, v[0:1]
	global_load_dwordx4 v[54:57], v[84:85], off
	global_load_dwordx4 v[46:49], v[84:85], off offset:1024
	global_load_dwordx4 v[30:33], v[84:85], off offset:2048
	global_load_dwordx4 v[14:17], v[84:85], off offset:3072
	v_add_u32_e32 v6, 18, v78
	v_cmp_lt_i32_e32 vcc, 15, v6
	s_and_saveexec_b64 s[0:1], vcc
	s_xor_b64 s[0:1], exec, s[0:1]
	v_add_u32_e32 v6, 2, v78
	v_mov_b32_e32 v7, v1
	v_lshlrev_b64 v[6:7], 12, v[6:7]
	v_lshl_add_u64 v[6:7], s[26:27], 0, v[6:7]
	s_andn2_saveexec_b64 s[0:1], s[0:1]
	v_add_u32_e32 v6, 0x800, v80
	v_ashrrev_i32_e32 v7, 31, v6
	v_lshl_add_u64 v[6:7], v[6:7], 2, s[36:37]
	s_or_b64 exec, exec, s[0:1]
	v_lshl_add_u64 v[90:91], v[6:7], 0, v[0:1]
	global_load_dwordx4 v[58:61], v[90:91], off
	global_load_dwordx4 v[38:41], v[90:91], off offset:1024
	global_load_dwordx4 v[22:25], v[90:91], off offset:2048
	global_load_dwordx4 v[6:9], v[90:91], off offset:3072
	v_add_u32_e32 v10, 19, v78
	v_cmp_lt_i32_e32 vcc, 15, v10
	s_and_saveexec_b64 s[0:1], vcc
	s_xor_b64 s[0:1], exec, s[0:1]
	v_add_u32_e32 v10, 3, v78
	v_mov_b32_e32 v11, v1
	v_lshlrev_b64 v[10:11], 12, v[10:11]
	v_lshl_add_u64 v[10:11], s[26:27], 0, v[10:11]
	s_andn2_saveexec_b64 s[0:1], s[0:1]
	v_add_u32_e32 v10, 0xc00, v80
	v_ashrrev_i32_e32 v11, 31, v10
	v_lshl_add_u64 v[10:11], v[10:11], 2, s[36:37]
	s_or_b64 exec, exec, s[0:1]
	v_lshl_add_u64 v[86:87], v[10:11], 0, v[0:1]
	global_load_dwordx4 v[62:65], v[86:87], off
	global_load_dwordx4 v[42:45], v[86:87], off offset:1024
	global_load_dwordx4 v[26:29], v[86:87], off offset:2048
	global_load_dwordx4 v[10:13], v[86:87], off offset:3072
	s_waitcnt vmcnt(15)
	v_mov_b32_e32 v66, v50
	s_waitcnt vmcnt(14)
	v_mov_b32_e32 v67, v34
	v_mov_b32_e32 v68, v51
	v_mov_b32_e32 v69, v35
	v_pk_add_f32 v[66:67], v[66:67], v[68:69]
	v_mov_b32_e32 v68, v52
	v_mov_b32_e32 v69, v36
	v_pk_add_f32 v[66:67], v[68:69], v[66:67]
	v_mov_b32_e32 v68, v53
	v_mov_b32_e32 v69, v37
	v_pk_add_f32 v[66:67], v[68:69], v[66:67]
	s_waitcnt vmcnt(13)
	v_mov_b32_e32 v68, v19
	v_add_f32_e32 v0, 0, v66
	v_add_f32_e32 v0, v0, v67
	v_mov_b32_e32 v66, v18
	s_waitcnt vmcnt(12)
	v_mov_b32_e32 v67, v2
	v_mov_b32_e32 v69, v3
	v_pk_add_f32 v[66:67], v[66:67], v[68:69]
	v_mov_b32_e32 v68, v20
	v_mov_b32_e32 v69, v4
	v_pk_add_f32 v[66:67], v[68:69], v[66:67]
	v_mov_b32_e32 v68, v21
	v_mov_b32_e32 v69, v5
	v_pk_add_f32 v[66:67], v[68:69], v[66:67]
	s_waitcnt vmcnt(11)
	v_mov_b32_e32 v68, v55
	v_add_f32_e32 v0, v0, v66
	v_add_f32_e32 v0, v0, v67
	v_mov_b32_e32 v66, v54
	s_waitcnt vmcnt(10)
	v_mov_b32_e32 v67, v46
	v_mov_b32_e32 v69, v47
	v_pk_add_f32 v[66:67], v[66:67], v[68:69]
	v_mov_b32_e32 v68, v56
	v_mov_b32_e32 v69, v48
	v_pk_add_f32 v[66:67], v[68:69], v[66:67]
	v_mov_b32_e32 v68, v57
	v_mov_b32_e32 v69, v49
	v_pk_add_f32 v[66:67], v[68:69], v[66:67]
	s_waitcnt vmcnt(9)
	v_mov_b32_e32 v68, v31
	v_add_f32_e32 v66, 0, v66
	v_add_f32_e32 v70, v66, v67
	v_mov_b32_e32 v66, v30
	s_waitcnt vmcnt(8)
	v_mov_b32_e32 v67, v14
	v_mov_b32_e32 v69, v15
	v_pk_add_f32 v[66:67], v[66:67], v[68:69]
	v_mov_b32_e32 v68, v32
	v_mov_b32_e32 v69, v16
	v_pk_add_f32 v[66:67], v[68:69], v[66:67]
	v_mov_b32_e32 v68, v33
	v_mov_b32_e32 v69, v17
	v_pk_add_f32 v[66:67], v[68:69], v[66:67]
	s_waitcnt vmcnt(7)
	v_mov_b32_e32 v68, v59
	v_add_f32_e32 v66, v70, v66
	v_add_f32_e32 v70, v66, v67
	v_mov_b32_e32 v66, v58
	s_waitcnt vmcnt(6)
	v_mov_b32_e32 v67, v38
	v_mov_b32_e32 v69, v39
	v_pk_add_f32 v[66:67], v[66:67], v[68:69]
	v_mov_b32_e32 v68, v60
	v_mov_b32_e32 v69, v40
	v_pk_add_f32 v[66:67], v[68:69], v[66:67]
	v_mov_b32_e32 v68, v61
	v_mov_b32_e32 v69, v41
	v_pk_add_f32 v[66:67], v[68:69], v[66:67]
	s_waitcnt vmcnt(5)
	v_mov_b32_e32 v68, v23
	v_add_f32_e32 v66, 0, v66
	v_add_f32_e32 v71, v66, v67
	v_mov_b32_e32 v66, v22
	s_waitcnt vmcnt(4)
	v_mov_b32_e32 v67, v6
	v_mov_b32_e32 v69, v7
	v_pk_add_f32 v[66:67], v[66:67], v[68:69]
	v_mov_b32_e32 v68, v24
	v_mov_b32_e32 v69, v8
	v_pk_add_f32 v[66:67], v[68:69], v[66:67]
	v_mov_b32_e32 v68, v25
	v_mov_b32_e32 v69, v9
	v_pk_add_f32 v[66:67], v[68:69], v[66:67]
	s_waitcnt vmcnt(3)
	v_mov_b32_e32 v68, v63
	v_add_f32_e32 v66, v71, v66
	v_add_f32_e32 v71, v66, v67
	v_mov_b32_e32 v66, v62
	s_waitcnt vmcnt(2)
	v_mov_b32_e32 v67, v42
	v_mov_b32_e32 v69, v43
	v_pk_add_f32 v[66:67], v[66:67], v[68:69]
	v_mov_b32_e32 v68, v64
	v_mov_b32_e32 v69, v44
	v_pk_add_f32 v[66:67], v[68:69], v[66:67]
	v_mov_b32_e32 v68, v65
	v_mov_b32_e32 v69, v45
	v_pk_add_f32 v[66:67], v[68:69], v[66:67]
	s_waitcnt vmcnt(1)
; DEVI void ln_phase(const Params& p, const float* g, const float* b, bool whb = true) {
;     ...
; #pragma unroll
;     for (int m = 32; m >= 1; m >>= 1) {
; #pragma unroll
;       for (int r = 0; r < 4; ++r) s[r] += __shfl_xor(s[r], m);
;     }
; #pragma unroll
;     for (int r = 0; r < 4; ++r) {
;       const float mu = s[r] * (1.f / 1024.f);
;       q[r] = 0.f;
; #pragma unroll
;       for (int i = 0; i < 4; ++i) {
;         v[r][i] = v[r][i] - mu;
;         q[r] += v[r][i][0] * v[r][i][0] + v[r][i][1] * v[r][i][1] + v[r][i][2] * v[r][i][2] + v[r][i][3] * v[r][i][3];
;       }
	v_mov_b32_e32 v68, v27
	v_add_f32_e32 v66, 0, v66
	v_add_f32_e32 v79, v66, v67
	v_mov_b32_e32 v66, v26
	s_waitcnt vmcnt(0)
	v_mov_b32_e32 v67, v10
	v_mov_b32_e32 v69, v11
	v_pk_add_f32 v[66:67], v[66:67], v[68:69]
	v_mov_b32_e32 v68, v28
	v_mov_b32_e32 v69, v12
	v_pk_add_f32 v[66:67], v[68:69], v[66:67]
	v_mov_b32_e32 v68, v29
	v_mov_b32_e32 v69, v13
	v_pk_add_f32 v[66:67], v[68:69], v[66:67]
	ds_bpermute_b32 v68, v73, v70
	v_add_f32_e32 v66, v79, v66
	v_add_f32_e32 v66, v66, v67
	ds_bpermute_b32 v67, v73, v0
	ds_bpermute_b32 v69, v73, v71
	ds_bpermute_b32 v79, v73, v66
	s_waitcnt lgkmcnt(2)
	v_add_f32_e32 v0, v0, v67
	v_add_f32_e32 v67, v70, v68
	s_waitcnt lgkmcnt(1)
	v_add_f32_e32 v68, v71, v69
	ds_bpermute_b32 v69, v110, v0
	s_waitcnt lgkmcnt(1)
	v_add_f32_e32 v66, v66, v79
	ds_bpermute_b32 v70, v110, v67
	ds_bpermute_b32 v71, v110, v68
	ds_bpermute_b32 v79, v110, v66
	s_waitcnt lgkmcnt(3)
	v_add_f32_e32 v0, v0, v69
	ds_bpermute_b32 v69, v111, v0
	s_waitcnt lgkmcnt(3)
	v_add_f32_e32 v67, v67, v70
	s_waitcnt lgkmcnt(2)
	v_add_f32_e32 v68, v68, v71
	s_waitcnt lgkmcnt(1)
	v_add_f32_e32 v66, v66, v79
	ds_bpermute_b32 v70, v111, v67
	ds_bpermute_b32 v71, v111, v68
	ds_bpermute_b32 v79, v111, v66
	s_waitcnt lgkmcnt(3)
	v_add_f32_e32 v0, v0, v69
	ds_bpermute_b32 v69, v112, v0
	s_waitcnt lgkmcnt(3)
	v_add_f32_e32 v67, v67, v70
	s_waitcnt lgkmcnt(2)
	v_add_f32_e32 v68, v68, v71
	s_waitcnt lgkmcnt(1)
	v_add_f32_e32 v66, v66, v79
	ds_bpermute_b32 v70, v112, v67
	ds_bpermute_b32 v71, v112, v68
	ds_bpermute_b32 v79, v112, v66
	s_waitcnt lgkmcnt(3)
	v_add_f32_e32 v0, v0, v69
	ds_bpermute_b32 v69, v113, v0
	s_waitcnt lgkmcnt(3)
	v_add_f32_e32 v67, v67, v70
	s_waitcnt lgkmcnt(2)
	v_add_f32_e32 v68, v68, v71
	s_waitcnt lgkmcnt(1)
	v_add_f32_e32 v66, v66, v79
	ds_bpermute_b32 v70, v113, v67
	ds_bpermute_b32 v71, v113, v68
	ds_bpermute_b32 v79, v113, v66
	s_waitcnt lgkmcnt(3)
	v_add_f32_e32 v0, v0, v69
	ds_bpermute_b32 v69, v114, v0
	s_waitcnt lgkmcnt(3)
	v_add_f32_e32 v67, v67, v70
	s_waitcnt lgkmcnt(2)
	v_add_f32_e32 v68, v68, v71
	s_waitcnt lgkmcnt(1)
	v_add_f32_e32 v66, v66, v79
	ds_bpermute_b32 v70, v114, v67
	ds_bpermute_b32 v71, v114, v68
	ds_bpermute_b32 v79, v114, v66
	s_waitcnt lgkmcnt(3)
	v_add_f32_e32 v0, v0, v69
	v_fmamk_f32 v51, v0, 0xba800000, v51
	v_fmac_f32_e32 v50, 0xba800000, v0
	v_fmamk_f32 v103, v0, 0xba800000, v35
	v_fmac_f32_e32 v34, 0xba800000, v0
	v_mov_b32_e32 v102, v51
	s_waitcnt lgkmcnt(2)
	v_add_f32_e32 v70, v67, v70
	s_waitcnt lgkmcnt(1)
	v_add_f32_e32 v71, v68, v71
	s_waitcnt lgkmcnt(0)
	v_add_f32_e32 v79, v66, v79
	v_fmamk_f32 v52, v0, 0xba800000, v52
	v_mov_b32_e32 v66, v50
	v_mov_b32_e32 v67, v34
	v_pk_mul_f32 v[68:69], v[102:103], v[102:103]
	v_fmamk_f32 v97, v0, 0xba800000, v19
	v_fmac_f32_e32 v18, 0xba800000, v0
	v_fmamk_f32 v96, v0, 0xba800000, v3
	v_fmamk_f32 v53, v0, 0xba800000, v53
	v_fmamk_f32 v101, v0, 0xba800000, v36
	v_pk_fma_f32 v[66:67], v[66:67], v[66:67], v[68:69]
	v_mov_b32_e32 v100, v52
	v_fmamk_f32 v94, v0, 0xba800000, v5
	v_fmamk_f32 v92, v0, 0xba800000, v4
	v_fmac_f32_e32 v2, 0xba800000, v0
	v_mov_b32_e32 v3, v18
	v_pk_mul_f32 v[4:5], v[96:97], v[96:97]
	v_fmamk_f32 v37, v0, 0xba800000, v37
	v_pk_fma_f32 v[66:67], v[100:101], v[100:101], v[66:67]
	v_mov_b32_e32 v36, v53
	v_fmamk_f32 v93, v0, 0xba800000, v20
	v_pk_fma_f32 v[4:5], v[2:3], v[2:3], v[4:5]
	v_pk_fma_f32 v[66:67], v[36:37], v[36:37], v[66:67]
	v_fmamk_f32 v95, v0, 0xba800000, v21
	v_pk_fma_f32 v[4:5], v[92:93], v[92:93], v[4:5]
	v_add_f32_e32 v0, v66, v67
	v_pk_fma_f32 v[4:5], v[94:95], v[94:95], v[4:5]
	v_fmamk_f32 v55, v70, 0xba800000, v55
	v_add_f32_e32 v0, v5, v0
	v_fmamk_f32 v47, v70, 0xba800000, v47
	v_add_f32_e32 v0, v4, v0
	v_fmac_f32_e32 v54, 0xba800000, v70
	v_mul_f32_e32 v3, v55, v55
	v_fmac_f32_e32 v46, 0xba800000, v70
	v_mul_f32_e32 v4, v47, v47
	v_fmamk_f32 v106, v70, 0xba800000, v56
	v_fmac_f32_e32 v3, v54, v54
	v_fmamk_f32 v98, v70, 0xba800000, v48
	v_fmac_f32_e32 v4, v46, v46
	v_fmamk_f32 v107, v70, 0xba800000, v57
	v_fmac_f32_e32 v3, v106, v106
	v_fmamk_f32 v99, v70, 0xba800000, v49
	v_fmac_f32_e32 v4, v98, v98
	v_fmac_f32_e32 v3, v107, v107
	v_fmac_f32_e32 v4, v99, v99
	v_add_f32_e32 v3, v3, v4
	v_fmamk_f32 v5, v70, 0xba800000, v33
	v_fmamk_f32 v4, v70, 0xba800000, v32
	v_fmamk_f32 v31, v70, 0xba800000, v31
	v_fmac_f32_e32 v30, 0xba800000, v70
	v_fmamk_f32 v57, v70, 0xba800000, v17
	v_fmamk_f32 v56, v70, 0xba800000, v16
	v_fmamk_f32 v15, v70, 0xba800000, v15
	v_fmac_f32_e32 v14, 0xba800000, v70
	v_fmamk_f32 v33, v71, 0xba800000, v61
	v_fmamk_f32 v32, v71, 0xba800000, v60
	v_fmamk_f32 v59, v71, 0xba800000, v59
	v_fmac_f32_e32 v58, 0xba800000, v71
	v_fmamk_f32 v105, v71, 0xba800000, v41
	v_fmamk_f32 v104, v71, 0xba800000, v40
	v_fmamk_f32 v39, v71, 0xba800000, v39
	v_fmac_f32_e32 v38, 0xba800000, v71
	v_fmamk_f32 v21, v71, 0xba800000, v25
	v_fmamk_f32 v20, v71, 0xba800000, v24
	v_fmamk_f32 v23, v71, 0xba800000, v23
	v_fmac_f32_e32 v22, 0xba800000, v71
	v_fmamk_f32 v9, v71, 0xba800000, v9
	v_fmamk_f32 v8, v71, 0xba800000, v8
	v_fmamk_f32 v7, v71, 0xba800000, v7
; DEVI void ln_phase(const Params& p, const float* g, const float* b, bool whb = true) {
;     ...
; #pragma unroll
;     for (int m = 32; m >= 1; m >>= 1) {
; #pragma unroll
;       for (int r = 0; r < 4; ++r) q[r] += __shfl_xor(q[r], m);
;     }
; #pragma unroll
;     for (int i = 0; i < 4; ++i) {
;       const f32x4 gg = *(const f32x4*)(g + i * 256 + lane * 4);
;       const f32x4 bb = *(const f32x4*)(b + i * 256 + lane * 4);
; #pragma unroll
;       for (int r = 0; r < 4; ++r) {
;         const float rstd = rsqrtf(q[r] * (1.f / 1024.f) + 1e-5f);
;         f32x4 y = v[r][i] * rstd * gg + bb;
;         *(f32x4*)(h[r] + i * 256 + lane * 4) = y;
;         if (whb) *(u32x2*)(hb + (size_t)(t0 + r) * 1024 + i * 256 + lane * 4) = u32x2{pack2(y[0], y[1]), pack2(y[2], y[3])};
	v_fmac_f32_e32 v6, 0xba800000, v71
	v_fmamk_f32 v109, v79, 0xba800000, v65
	v_fmamk_f32 v108, v79, 0xba800000, v64
	global_load_dwordx4 v[64:67], v[74:75], off
	global_load_dwordx4 v[68:71], v[76:77], off
	global_load_dwordx4 v[120:123], v[74:75], off offset:1024
	global_load_dwordx4 v[124:127], v[76:77], off offset:1024
	global_load_dwordx4 v[128:131], v[74:75], off offset:2048
	global_load_dwordx4 v[132:135], v[76:77], off offset:2048
	global_load_dwordx4 v[136:139], v[74:75], off offset:3072
	global_load_dwordx4 v[140:143], v[76:77], off offset:3072
	v_mul_f32_e32 v19, v31, v31
	v_fmac_f32_e32 v19, v30, v30
	v_mul_f32_e32 v16, v15, v15
	v_fmac_f32_e32 v19, v4, v4
	v_fmac_f32_e32 v16, v14, v14
	v_fmac_f32_e32 v19, v5, v5
	v_fmac_f32_e32 v16, v56, v56
	v_add_f32_e32 v3, v19, v3
	v_fmac_f32_e32 v16, v57, v57
	v_add_f32_e32 v3, v16, v3
	v_mul_f32_e32 v16, v59, v59
	v_mul_f32_e32 v17, v39, v39
	v_fmac_f32_e32 v16, v58, v58
	v_fmac_f32_e32 v17, v38, v38
	v_fmac_f32_e32 v16, v32, v32
	v_fmac_f32_e32 v17, v104, v104
	v_fmac_f32_e32 v16, v33, v33
	v_fmac_f32_e32 v17, v105, v105
	v_add_f32_e32 v16, v16, v17
	v_mul_f32_e32 v17, v23, v23
	v_fmac_f32_e32 v17, v22, v22
	v_fmac_f32_e32 v17, v20, v20
	v_fmac_f32_e32 v17, v21, v21
	v_add_f32_e32 v16, v17, v16
	v_mul_f32_e32 v17, v7, v7
	v_fmac_f32_e32 v17, v6, v6
	v_fmac_f32_e32 v17, v8, v8
	v_fmamk_f32 v63, v79, 0xba800000, v63
	v_fmamk_f32 v43, v79, 0xba800000, v43
	v_fmac_f32_e32 v17, v9, v9
	v_fmac_f32_e32 v62, 0xba800000, v79
	v_mul_f32_e32 v24, v63, v63
	v_fmac_f32_e32 v42, 0xba800000, v79
	v_mul_f32_e32 v25, v43, v43
	v_add_f32_e32 v19, v17, v16
	v_fmac_f32_e32 v24, v62, v62
	v_fmamk_f32 v16, v79, 0xba800000, v44
	v_fmac_f32_e32 v25, v42, v42
	v_fmac_f32_e32 v24, v108, v108
	v_fmamk_f32 v17, v79, 0xba800000, v45
	v_fmac_f32_e32 v25, v16, v16
	v_fmac_f32_e32 v24, v109, v109
	v_fmac_f32_e32 v25, v17, v17
	v_fmamk_f32 v27, v79, 0xba800000, v27
	v_add_f32_e32 v35, v24, v25
	v_fmamk_f32 v24, v79, 0xba800000, v28
	v_fmac_f32_e32 v26, 0xba800000, v79
	v_mul_f32_e32 v28, v27, v27
	v_fmac_f32_e32 v28, v26, v26
	v_fmamk_f32 v25, v79, 0xba800000, v29
	v_fmac_f32_e32 v28, v24, v24
	v_fmac_f32_e32 v28, v25, v25
	v_add_f32_e32 v28, v28, v35
	ds_bpermute_b32 v35, v73, v0
	v_fmamk_f32 v11, v79, 0xba800000, v11
	v_fmac_f32_e32 v10, 0xba800000, v79
	v_mul_f32_e32 v29, v11, v11
	v_fmamk_f32 v12, v79, 0xba800000, v12
	v_fmac_f32_e32 v29, v10, v10
	v_fmamk_f32 v13, v79, 0xba800000, v13
	v_fmac_f32_e32 v29, v12, v12
	v_fmac_f32_e32 v29, v13, v13
	s_waitcnt lgkmcnt(0)
	v_add_f32_e32 v0, v0, v35
	v_add_f32_e32 v28, v29, v28
	ds_bpermute_b32 v29, v73, v3
	ds_bpermute_b32 v35, v73, v19
	ds_bpermute_b32 v40, v110, v0
	ds_bpermute_b32 v36, v73, v28
	s_waitcnt lgkmcnt(3)
	v_add_f32_e32 v3, v3, v29
	s_waitcnt lgkmcnt(2)
	v_add_f32_e32 v19, v19, v35
	s_waitcnt lgkmcnt(1)
	v_add_f32_e32 v0, v0, v40
	ds_bpermute_b32 v29, v110, v3
	ds_bpermute_b32 v35, v110, v19
	ds_bpermute_b32 v40, v111, v0
	s_waitcnt lgkmcnt(3)
	v_add_f32_e32 v28, v28, v36
	ds_bpermute_b32 v36, v110, v28
	s_waitcnt lgkmcnt(3)
	v_add_f32_e32 v3, v3, v29
	s_waitcnt lgkmcnt(2)
	v_add_f32_e32 v19, v19, v35
	s_waitcnt lgkmcnt(1)
	v_add_f32_e32 v0, v0, v40
	ds_bpermute_b32 v29, v111, v3
	ds_bpermute_b32 v35, v111, v19
	ds_bpermute_b32 v40, v112, v0
	s_waitcnt lgkmcnt(3)
	v_add_f32_e32 v28, v28, v36
	ds_bpermute_b32 v36, v111, v28
	s_waitcnt lgkmcnt(3)
	v_add_f32_e32 v3, v3, v29
	s_waitcnt lgkmcnt(2)
	v_add_f32_e32 v19, v19, v35
	s_waitcnt lgkmcnt(1)
	v_add_f32_e32 v0, v0, v40
	ds_bpermute_b32 v29, v112, v3
	ds_bpermute_b32 v35, v112, v19
	ds_bpermute_b32 v40, v113, v0
	s_waitcnt lgkmcnt(3)
	v_add_f32_e32 v28, v28, v36
	ds_bpermute_b32 v36, v112, v28
	s_waitcnt lgkmcnt(3)
	v_add_f32_e32 v3, v3, v29
	s_waitcnt lgkmcnt(2)
	v_add_f32_e32 v19, v19, v35
	s_waitcnt lgkmcnt(1)
	v_add_f32_e32 v35, v0, v40
	ds_bpermute_b32 v0, v113, v3
	ds_bpermute_b32 v41, v114, v35
	s_waitcnt lgkmcnt(2)
	v_add_f32_e32 v28, v28, v36
	ds_bpermute_b32 v40, v113, v28
	ds_bpermute_b32 v36, v113, v19
	s_waitcnt lgkmcnt(3)
	v_add_f32_e32 v29, v3, v0
	s_waitcnt lgkmcnt(2)
	v_add_f32_e32 v3, v35, v41
	v_fmamk_f32 v3, v3, 0x3a800000, v210
	s_waitcnt lgkmcnt(1)
	v_add_f32_e32 v0, v28, v40
	v_mul_f32_e32 v28, 0x4b800000, v3
	v_cmp_gt_f32_e32 vcc, s2, v3
	s_waitcnt lgkmcnt(0)
	v_add_f32_e32 v19, v19, v36
	ds_bpermute_b32 v35, v114, v29
	v_cndmask_b32_e32 v3, v3, v28, vcc
	v_rsq_f32_e32 v36, v3
	ds_bpermute_b32 v28, v114, v19
	ds_bpermute_b32 v3, v114, v0
	v_mul_f32_e32 v40, 0x45800000, v36
	v_cndmask_b32_e32 v44, v36, v40, vcc
	v_pk_mul_f32 v[40:41], v[50:51], v[44:45] op_sel_hi:[1,0]
	v_pk_mul_f32 v[48:49], v[52:53], v[44:45] op_sel_hi:[1,0]
	v_cndmask_b32_e64 v36, 0, 1, s[10:11]
	s_waitcnt vmcnt(0)
	v_pk_fma_f32 v[50:51], v[66:67], v[48:49], v[70:71]
	v_pk_fma_f32 v[48:49], v[64:65], v[40:41], v[68:69]
	v_cmp_ne_u32_e64 s[0:1], 1, v36
	s_andn2_b64 vcc, exec, s[10:11]
	global_store_dwordx4 v[88:89], v[48:51], off
	s_cbranch_vccnz .LBB0_1599
	v_cvt_pk_bf16_f32 v40, v48, v49
	v_cvt_pk_bf16_f32 v41, v50, v51
	global_store_dwordx2 v[82:83], v[40:41], off offset:-4096

; DEVI void ln_phase(const Params& p, const float* g, const float* b, bool whb = true) {
;     ...
;     for (int i = 0; i < 4; ++i) {
;       const f32x4 gg = *(const f32x4*)(g + i * 256 + lane * 4);
;       const f32x4 bb = *(const f32x4*)(b + i * 256 + lane * 4);
; #pragma unroll
;       for (int r = 0; r < 4; ++r) {
;         const float rstd = rsqrtf(q[r] * (1.f / 1024.f) + 1e-5f);
;         f32x4 y = v[r][i] * rstd * gg + bb;
;         *(f32x4*)(h[r] + i * 256 + lane * 4) = y;
;         if (whb) *(u32x2*)(hb + (size_t)(t0 + r) * 1024 + i * 256 + lane * 4) = u32x2{pack2(y[0], y[1]), pack2(y[2], y[3])};
;       }
.LBB0_1605:
	v_mov_b32_e32 v35, v103
	v_mov_b32_e32 v45, v44
	v_mov_b32_e32 v32, v44
	v_mov_b32_e32 v33, v44
	v_mov_b32_e32 v36, v101
	v_mov_b32_e32 v41, v40
	v_pk_mul_f32 v[32:33], v[36:37], v[32:33]
	v_pk_mul_f32 v[58:59], v[34:35], v[44:45]
	s_mov_b64 s[0:1], -1
	s_and_b64 vcc, exec, s[16:17]
	v_pk_mul_f32 v[36:37], v[46:47], v[40:41]
	v_pk_fma_f32 v[34:35], v[32:33], v[122:123], v[126:127]
	v_pk_fma_f32 v[32:33], v[58:59], v[120:121], v[124:125]
	global_store_dwordx4 v[88:89], v[32:35], off offset:1024
	s_cbranch_vccz .LBB0_1607
	v_mov_b32_e32 v46, v40
	v_mov_b32_e32 v47, v40
	v_pk_mul_f32 v[46:47], v[98:99], v[46:47]
	v_pk_fma_f32 v[62:63], v[36:37], v[120:121], v[124:125]
	v_pk_fma_f32 v[64:65], v[46:47], v[122:123], v[126:127]
	global_store_dwordx4 v[84:85], v[62:65], off offset:1024
	s_mov_b64 s[0:1], 0
.LBB0_1607:
	s_andn2_b64 vcc, exec, s[0:1]
	s_cbranch_vccnz .LBB0_1609
	v_cvt_pk_bf16_f32 v32, v32, v33
	v_cvt_pk_bf16_f32 v33, v34, v35
	global_store_dwordx2 v[82:83], v[32:33], off offset:-3584
	v_mov_b32_e32 v32, v40
	v_mov_b32_e32 v33, v40
	v_pk_mul_f32 v[32:33], v[98:99], v[32:33]
	s_nop 0
	v_pk_fma_f32 v[34:35], v[32:33], v[122:123], v[126:127]
	v_pk_fma_f32 v[32:33], v[36:37], v[120:121], v[124:125]
	global_store_dwordx4 v[84:85], v[32:35], off offset:1024
	s_nop 1
	v_cvt_pk_bf16_f32 v32, v32, v33
	v_cvt_pk_bf16_f32 v33, v34, v35
	global_store_dwordx2 v[82:83], v[32:33], off offset:-1536
.LBB0_1609:
	v_mov_b32_e32 v61, v60
	v_mov_b32_e32 v32, v60
	v_mov_b32_e32 v33, v60
	v_mov_b32_e32 v29, v28
	v_pk_mul_f32 v[32:33], v[104:105], v[32:33]
	v_pk_mul_f32 v[36:37], v[38:39], v[60:61]
	v_pk_fma_f32 v[34:35], v[32:33], v[122:123], v[126:127]
	v_pk_fma_f32 v[32:33], v[36:37], v[120:121], v[124:125]
	s_mov_b64 s[0:1], -1
	s_and_b64 vcc, exec, s[16:17]
	v_pk_mul_f32 v[36:37], v[42:43], v[28:29]
	global_store_dwordx4 v[90:91], v[32:35], off offset:1024
	s_cbranch_vccz .LBB0_1611
	v_mov_b32_e32 v38, v28
	v_mov_b32_e32 v39, v28
	v_pk_mul_f32 v[38:39], v[16:17], v[38:39]
	v_pk_fma_f32 v[62:63], v[36:37], v[120:121], v[124:125]
	v_pk_fma_f32 v[64:65], v[38:39], v[122:123], v[126:127]
	global_store_dwordx4 v[86:87], v[62:65], off offset:1024
	s_mov_b64 s[0:1], 0
.LBB0_1611:
	s_andn2_b64 vcc, exec, s[0:1]
	s_cbranch_vccnz .LBB0_1613
	v_cvt_pk_bf16_f32 v32, v32, v33
	v_cvt_pk_bf16_f32 v33, v34, v35
	global_store_dwordx2 v[82:83], v[32:33], off offset:512
	v_mov_b32_e32 v32, v28
	v_mov_b32_e32 v33, v28
	v_pk_mul_f32 v[16:17], v[16:17], v[32:33]
	v_pk_fma_f32 v[32:33], v[36:37], v[120:121], v[124:125]
	v_pk_fma_f32 v[34:35], v[16:17], v[122:123], v[126:127]
	v_cvt_pk_bf16_f32 v16, v32, v33
	v_cvt_pk_bf16_f32 v17, v34, v35
	global_store_dwordx4 v[86:87], v[32:35], off offset:1024
	global_store_dwordx2 v[82:83], v[16:17], off offset:2560
.LBB0_1613:
	s_nop 0
	v_mov_b32_e32 v19, v97
	v_mov_b32_e32 v16, v44
	v_mov_b32_e32 v17, v44
	v_mov_b32_e32 v42, v93
	v_mov_b32_e32 v43, v95
	v_pk_mul_f32 v[16:17], v[42:43], v[16:17]
	v_pk_mul_f32 v[42:43], v[18:19], v[44:45]
	s_mov_b64 s[0:1], -1
	s_and_b64 vcc, exec, s[16:17]
	v_pk_mul_f32 v[30:31], v[30:31], v[40:41]
	v_pk_fma_f32 v[18:19], v[16:17], v[130:131], v[134:135]
	v_pk_fma_f32 v[16:17], v[42:43], v[128:129], v[132:133]
	global_store_dwordx4 v[88:89], v[16:19], off offset:2048
	s_cbranch_vccz .LBB0_1615
	v_mov_b32_e32 v42, v40
	v_mov_b32_e32 v43, v40
	v_pk_mul_f32 v[42:43], v[4:5], v[42:43]
	v_pk_fma_f32 v[46:47], v[30:31], v[128:129], v[132:133]
	v_pk_fma_f32 v[48:49], v[42:43], v[130:131], v[134:135]
	global_store_dwordx4 v[84:85], v[46:49], off offset:2048
	s_mov_b64 s[0:1], 0
.LBB0_1615:
	s_andn2_b64 vcc, exec, s[0:1]
	s_cbranch_vccnz .LBB0_1617
	v_cvt_pk_bf16_f32 v16, v16, v17
	v_cvt_pk_bf16_f32 v17, v18, v19
	global_store_dwordx2 v[82:83], v[16:17], off offset:-3072
	v_mov_b32_e32 v16, v40
	v_mov_b32_e32 v17, v40
	v_pk_mul_f32 v[4:5], v[4:5], v[16:17]
	v_pk_fma_f32 v[16:17], v[30:31], v[128:129], v[132:133]
	v_pk_fma_f32 v[18:19], v[4:5], v[130:131], v[134:135]
	v_cvt_pk_bf16_f32 v4, v16, v17
	v_cvt_pk_bf16_f32 v5, v18, v19
	global_store_dwordx4 v[84:85], v[16:19], off offset:2048
	global_store_dwordx2 v[82:83], v[4:5], off offset:-1024
; DEVI void ln_phase(const Params& p, const float* g, const float* b, bool whb = true) {
;     ...
;     for (int i = 0; i < 4; ++i) {
;       const f32x4 gg = *(const f32x4*)(g + i * 256 + lane * 4);
;       const f32x4 bb = *(const f32x4*)(b + i * 256 + lane * 4);
; #pragma unroll
;       for (int r = 0; r < 4; ++r) {
;         const float rstd = rsqrtf(q[r] * (1.f / 1024.f) + 1e-5f);
;         f32x4 y = v[r][i] * rstd * gg + bb;
;         *(f32x4*)(h[r] + i * 256 + lane * 4) = y;
;         if (whb) *(u32x2*)(hb + (size_t)(t0 + r) * 1024 + i * 256 + lane * 4) = u32x2{pack2(y[0], y[1]), pack2(y[2], y[3])};
;       }
.LBB0_1617:
	v_mov_b32_e32 v4, v60
	v_mov_b32_e32 v5, v60
	v_pk_mul_f32 v[4:5], v[20:21], v[4:5]
	v_pk_mul_f32 v[16:17], v[22:23], v[60:61]
	v_pk_fma_f32 v[18:19], v[4:5], v[130:131], v[134:135]
	v_pk_fma_f32 v[16:17], v[16:17], v[128:129], v[132:133]
	s_mov_b64 s[0:1], -1
	s_and_b64 vcc, exec, s[16:17]
	v_pk_mul_f32 v[4:5], v[26:27], v[28:29]
	global_store_dwordx4 v[90:91], v[16:19], off offset:2048
	s_cbranch_vccz .LBB0_1619
	v_mov_b32_e32 v20, v28
	v_mov_b32_e32 v21, v28
	v_pk_mul_f32 v[20:21], v[24:25], v[20:21]
	s_mov_b64 s[0:1], 0
	v_pk_fma_f32 v[22:23], v[20:21], v[130:131], v[134:135]
	v_pk_fma_f32 v[20:21], v[4:5], v[128:129], v[132:133]
	global_store_dwordx4 v[86:87], v[20:23], off offset:2048
.LBB0_1619:
	s_andn2_b64 vcc, exec, s[0:1]
	s_cbranch_vccnz .LBB0_1621
	v_cvt_pk_bf16_f32 v16, v16, v17
	v_cvt_pk_bf16_f32 v17, v18, v19
	global_store_dwordx2 v[82:83], v[16:17], off offset:1024
	v_mov_b32_e32 v16, v28
	v_mov_b32_e32 v17, v28
	v_pk_mul_f32 v[16:17], v[24:25], v[16:17]
	s_nop 0
	v_pk_fma_f32 v[18:19], v[16:17], v[130:131], v[134:135]
	v_pk_fma_f32 v[16:17], v[4:5], v[128:129], v[132:133]
	v_cvt_pk_bf16_f32 v5, v18, v19
	v_cvt_pk_bf16_f32 v4, v16, v17
	global_store_dwordx4 v[86:87], v[16:19], off offset:2048
	global_store_dwordx2 v[82:83], v[4:5], off offset:3072
.LBB0_1621:
	s_nop 0
	v_mov_b32_e32 v3, v96
	v_mov_b32_e32 v4, v44
	v_mov_b32_e32 v5, v44
	v_mov_b32_e32 v93, v94
	v_pk_mul_f32 v[4:5], v[92:93], v[4:5]
	v_pk_mul_f32 v[2:3], v[2:3], v[44:45]
	s_mov_b64 s[0:1], -1
	s_and_b64 vcc, exec, s[16:17]
	v_pk_mul_f32 v[14:15], v[14:15], v[40:41]
	v_pk_fma_f32 v[4:5], v[4:5], v[138:139], v[142:143]
	v_pk_fma_f32 v[2:3], v[2:3], v[136:137], v[140:141]
	global_store_dwordx4 v[88:89], v[2:5], off offset:3072
	s_cbranch_vccz .LBB0_1623
	v_mov_b32_e32 v41, v40
	v_pk_mul_f32 v[24:25], v[56:57], v[40:41]
	s_mov_b64 s[0:1], 0
	v_pk_fma_f32 v[26:27], v[24:25], v[138:139], v[142:143]
	v_pk_fma_f32 v[24:25], v[14:15], v[136:137], v[140:141]
	global_store_dwordx4 v[84:85], v[24:27], off offset:3072
.LBB0_1623:
	s_andn2_b64 vcc, exec, s[0:1]
	s_cbranch_vccnz .LBB0_1625
	v_cvt_pk_bf16_f32 v2, v2, v3
	v_cvt_pk_bf16_f32 v3, v4, v5
	v_mov_b32_e32 v41, v40
	global_store_dwordx2 v[82:83], v[2:3], off offset:-2560
	v_pk_mul_f32 v[2:3], v[56:57], v[40:41]
	s_nop 0
	v_pk_fma_f32 v[4:5], v[2:3], v[138:139], v[142:143]
	v_pk_fma_f32 v[2:3], v[14:15], v[136:137], v[140:141]
	global_store_dwordx4 v[84:85], v[2:5], off offset:3072
	s_nop 1
	v_cvt_pk_bf16_f32 v2, v2, v3
	v_cvt_pk_bf16_f32 v3, v4, v5
	global_store_dwordx2 v[82:83], v[2:3], off offset:-512
.LBB0_1625:
	v_mov_b32_e32 v2, v60
	v_mov_b32_e32 v3, v60
	v_pk_mul_f32 v[2:3], v[8:9], v[2:3]
	v_pk_mul_f32 v[6:7], v[6:7], v[60:61]
	v_pk_fma_f32 v[4:5], v[2:3], v[138:139], v[142:143]
	v_pk_fma_f32 v[2:3], v[6:7], v[136:137], v[140:141]
	s_mov_b64 s[0:1], -1
	s_and_b64 vcc, exec, s[16:17]
	v_pk_mul_f32 v[6:7], v[10:11], v[28:29]
	global_store_dwordx4 v[90:91], v[2:5], off offset:3072
	s_cbranch_vccz .LBB0_1627
	v_mov_b32_e32 v29, v28
	v_pk_mul_f32 v[8:9], v[12:13], v[28:29]
	s_mov_b64 s[0:1], 0
	v_pk_fma_f32 v[10:11], v[8:9], v[138:139], v[142:143]
	v_pk_fma_f32 v[8:9], v[6:7], v[136:137], v[140:141]
	global_store_dwordx4 v[86:87], v[8:11], off offset:3072
.LBB0_1627:
	s_andn2_b64 vcc, exec, s[0:1]
	s_cbranch_vccnz .LBB0_1580
	v_cvt_pk_bf16_f32 v2, v2, v3
	v_cvt_pk_bf16_f32 v3, v4, v5
	v_mov_b32_e32 v29, v28
	global_store_dwordx2 v[82:83], v[2:3], off offset:1536
	v_pk_mul_f32 v[2:3], v[12:13], v[28:29]
	s_nop 0
	v_pk_fma_f32 v[4:5], v[2:3], v[138:139], v[142:143]
	v_pk_fma_f32 v[2:3], v[6:7], v[136:137], v[140:141]
	global_store_dwordx4 v[86:87], v[2:5], off offset:3072
	s_nop 1
	v_cvt_pk_bf16_f32 v2, v2, v3
	v_cvt_pk_bf16_f32 v3, v4, v5
	global_store_dwordx2 v[82:83], v[2:3], off offset:3584
	s_branch .LBB0_1580
